# v79 + attention unit top waits only for its prefetched loads (vmcnt(3), the three O/lse stores stay in flight); loop entry drains with vmcnt(0)
# baseline (speedup 1.0000x reference)
.LBB0_34:
	v_lshlrev_b32_e32 v21, 1, v200
	v_lshlrev_b32_e32 v22, 2, v196
	v_lshrrev_b32_e32 v23, 1, v196
	v_and_b32_e32 v22, 24, v22
	v_and_b32_e32 v23, 4, v23
	v_and_b32_e32 v21, 0x62, v21
	s_waitcnt lgkmcnt(0)
	v_lshl_add_u32 v72, v20, 4, 0
	v_or3_b32 v77, v23, v22, v21
	v_mad_u64_u32 v[20:21], s[4:5], v73, s81, v[72:73]
	s_waitcnt vmcnt(2)
	ds_write_b128 v20, v[10:13] offset:9216
	v_lshlrev_b32_e32 v10, 5, v19
	v_ashrrev_i32_e32 v11, 5, v196
	v_and_b32_e32 v10, 32, v10
	v_and_b32_e32 v11, 0xffffffc, v11
	v_add_u32_e32 v10, v10, v11
	s_movk_i32 s4, 0x210
	v_mul_lo_u32 v10, v10, s4
	v_add_u32_e32 v78, 0, v10
	s_waitcnt vmcnt(0)
	v_lshlrev_b32_e32 v11, 16, v6
	s_mov_b32 s4, 0xffff
	v_lshl_add_u32 v10, v77, 1, v78
	v_and_or_b32 v11, v2, s4, v11
	v_lshrrev_b32_e32 v2, 16, v2
	v_and_or_b32 v2, v6, s22, v2
	v_add_u32_e32 v6, 0x9000, v10
	ds_write_b128 v20, v[14:17]
	ds_write2_b32 v6, v11, v2 offset1:132
	v_lshlrev_b32_e32 v2, 16, v7
	v_and_or_b32 v2, v3, s4, v2
	v_lshrrev_b32_e32 v3, 16, v3
	s_lshl_b32 s71, 1, s7
	s_lshl_b32 s70, s6, 13
	v_and_or_b32 v3, v7, s22, v3
	v_add_u32_e32 v6, 0x9400, v10
	s_add_u32 s33, s34, 0xdc00000
	ds_write2_b32 v6, v2, v3 offset0:8 offset1:140
	v_lshlrev_b32_e32 v2, 16, v8
	v_lshrrev_b32_e32 v3, 16, v4
	s_addc_u32 s36, s35, 0
	v_and_or_b32 v2, v4, s4, v2
	v_and_or_b32 v3, v8, s22, v3
	v_add_u32_e32 v4, 0xb000, v10
	s_add_u32 s44, s34, 0x11c00000
	ds_write2_b32 v4, v2, v3 offset0:64 offset1:196
	v_lshlrev_b32_e32 v2, 16, v9
	s_addc_u32 s45, s35, 0
	v_and_or_b32 v2, v5, s4, v2
	v_lshrrev_b32_e32 v3, 16, v5
	s_lshl_b32 s4, s21, 4
	s_lshl_b32 s5, s69, 7
	v_and_b32_e32 v22, 15, v196
	v_and_or_b32 v3, v9, s22, v3
	v_add_u32_e32 v4, 0xb400, v10
	s_add_i32 s5, s5, s4
	v_lshrrev_b32_e32 v23, 4, v200
	ds_write2_b32 v4, v2, v3 offset0:72 offset1:204
	v_or_b32_e32 v2, s5, v22
	v_lshlrev_b32_e32 v20, 3, v23
	v_lshlrev_b32_e32 v2, 6, v2
	v_add3_u32 v2, s28, v20, v2
	v_ashrrev_i32_e32 v3, 31, v2
	v_lshl_add_u64 v[2:3], v[2:3], 1, s[78:79]
	v_add_u32_e32 v16, s28, v18
	global_load_dwordx4 v[44:47], v[2:3], off offset:64
	global_load_dwordx4 v[52:55], v[2:3], off
	v_add_u32_e32 v2, v16, v76
	v_lshlrev_b32_e32 v14, 6, v73
	v_or_b32_e32 v79, s4, v22
	v_ashrrev_i32_e32 v3, 31, v2
	s_movk_i32 s4, 0x1000
	v_lshl_add_u64 v[2:3], v[2:3], 1, s[42:43]
	v_add3_u32 v80, v14, v1, s4
	global_load_dwordx4 v[4:7], v[2:3], off offset:128
	global_load_dwordx4 v[8:11], v[2:3], off
	v_add_u32_e32 v2, v16, v80
	v_ashrrev_i32_e32 v3, 31, v2
	v_lshl_add_u64 v[2:3], v[2:3], 1, s[0:1]
	global_load_dwordx4 v[12:15], v[2:3], off
	v_add_u32_e32 v2, v16, v75
	v_ashrrev_i32_e32 v3, 31, v2
	v_lshl_add_u64 v[2:3], v[2:3], 1, s[0:1]
	global_load_dwordx4 v[16:19], v[2:3], off
	v_mul_u32_u24_e32 v1, 0x90, v22
	v_and_b32_e32 v81, 48, v196
	v_add3_u32 v74, 0, v1, v81
	v_lshlrev_b32_e32 v1, 2, v23
	v_sub_u32_e32 v1, v1, v22
	s_bitcmp1_b32 s21, 0
	s_movk_i32 s4, 0x180
	s_cselect_b64 s[46:47], -1, 0
	v_mad_u32_u24 v82, v22, s4, v74
	v_cmp_gt_u32_e64 s[4:5], 16, v200
	s_mov_b32 s48, 0
	v_cmp_gt_i32_e64 s[6:7], 0, v1
	v_cmp_lt_i32_e64 s[8:9], 0, v1
	v_cmp_gt_i32_e64 s[10:11], -1, v1
	v_cmp_gt_i32_e64 s[12:13], -2, v1
	v_cmp_lt_i32_e64 s[14:15], -2, v1
	v_cmp_gt_i32_e64 s[16:17], -3, v1
	v_cmp_lt_i32_e64 s[18:19], -3, v1
	v_lshl_or_b32 v83, v79, 6, v20
	s_mov_b32 s37, s2
	s_waitcnt vmcnt(0)
	s_branch .LBB0_36

.LBB0_38:
	s_xor_b32 s24, s48, 1
	s_lshl_b32 s49, s24, 7
	v_add_u32_e32 v1, s49, v73
	v_mad_u64_u32 v[2:3], s[26:27], v1, s81, v[72:73]
	v_or_b32_e32 v1, s49, v77
	s_waitcnt vmcnt(3)
	ds_write_b128 v2, v[16:19]
	ds_write_b128 v2, v[12:15] offset:9216
	v_lshl_add_u32 v1, v1, 1, v78
	v_and_b32_e32 v2, 0xffff, v8
	v_lshrrev_b32_e32 v3, 16, v8
	v_lshl_or_b32 v2, v4, 16, v2
	v_and_or_b32 v3, v4, s22, v3
	v_add_u32_e32 v20, 0x9000, v1
	ds_write2_b32 v20, v2, v3 offset1:132
	v_and_b32_e32 v2, 0xffff, v9
	v_lshrrev_b32_e32 v3, 16, v9
	v_lshl_or_b32 v2, v5, 16, v2
	v_and_or_b32 v3, v5, s22, v3
	v_add_u32_e32 v20, 0x9400, v1
	ds_write2_b32 v20, v2, v3 offset0:8 offset1:140
	v_and_b32_e32 v2, 0xffff, v10
	v_lshrrev_b32_e32 v3, 16, v10
	s_add_i32 s37, s37, 1
	v_lshl_or_b32 v2, v6, 16, v2
	v_and_or_b32 v3, v6, s22, v3
	v_add_u32_e32 v20, 0xb000, v1
	s_cmp_ge_i32 s37, s3
	ds_write2_b32 v20, v2, v3 offset0:64 offset1:196
	v_and_b32_e32 v2, 0xffff, v11
	v_lshrrev_b32_e32 v3, 16, v11
	s_cselect_b64 s[26:27], -1, 0
	v_mov_b64_e32 v[20:21], v[44:45]
	v_mov_b64_e32 v[24:25], v[52:53]
	v_lshl_or_b32 v2, v7, 16, v2
	v_and_or_b32 v3, v7, s22, v3
	v_add_u32_e32 v1, 0xb400, v1
	s_and_b64 vcc, exec, s[26:27]
	s_mov_b32 s54, s69
	s_mov_b32 s63, s71
	s_mov_b32 s61, s67
	s_mov_b32 s53, s31
	s_mov_b32 s52, s29
	s_mov_b32 s66, s70
	s_mov_b32 s62, s28
	v_mov_b64_e32 v[22:23], v[46:47]
	v_mov_b64_e32 v[26:27], v[54:55]
	ds_write2_b32 v1, v2, v3 offset0:72 offset1:204
	s_waitcnt lgkmcnt(0)
	s_barrier
	s_cbranch_vccnz .LBB0_40
	s_ashr_i32 s53, s37, 9
	s_mul_hi_i32 s54, s53, 0x55555556
	s_lshr_b32 s57, s54, 31
	s_add_i32 s57, s54, s57
	s_mul_i32 s54, s57, 3
	s_sub_i32 s53, s53, s54
	s_lshl_b32 s60, s53, 1
	s_lshr_b32 s54, 64, s60
	s_and_b32 s49, s37, 63
	s_sub_i32 s61, 6, s60
	s_add_i32 s54, s54, -1
	s_lshr_b32 s61, s49, s61
	s_and_b32 s54, s54, s49
	s_lshl_b32 s49, s53, 3
	s_mul_i32 s62, s57, 24
	s_bfe_u32 s52, s37, 0x30006
	s_add_i32 s62, s62, s49
	s_or_b32 s49, s62, s52
	s_lshl_b32 s49, s49, s60
	s_add_i32 s49, s49, s61
	s_sub_i32 s62, 19, s60
	s_lshl_b32 s62, s49, s62
	s_lshl_b32 s49, s54, 13
	s_add_i32 s49, s62, s49
	v_add_u32_e32 v2, s49, v75
	v_ashrrev_i32_e32 v3, 31, v2
	v_add_u32_e32 v4, s49, v80
	v_lshl_add_u64 v[2:3], v[2:3], 1, s[0:1]
	v_ashrrev_i32_e32 v5, 31, v4
	v_lshl_add_u64 v[4:5], v[4:5], 1, s[0:1]
	global_load_dwordx4 v[16:19], v[2:3], off
	global_load_dwordx4 v[12:15], v[4:5], off
	v_add_u32_e32 v2, s49, v76
	v_ashrrev_i32_e32 v3, 31, v2
	v_lshl_add_u64 v[2:3], v[2:3], 1, s[42:43]
	global_load_dwordx4 v[8:11], v[2:3], off
	global_load_dwordx4 v[4:7], v[2:3], off offset:128
	v_add_u32_e32 v2, s49, v83
	v_ashrrev_i32_e32 v3, 31, v2
	v_lshl_add_u64 v[2:3], v[2:3], 1, s[78:79]
	global_load_dwordx4 v[24:27], v[2:3], off
	global_load_dwordx4 v[20:23], v[2:3], off offset:64
	s_lshl_b32 s63, 1, s60
	s_lshl_b32 s66, s57, 13
